# GEMM phase prologues (P1, P3, P4, P5): the second group of LDS-DMA stages (K-step 1 buffers) is issued together with the first group, before the stagger barrier and the first counted wait (now vmcnt(8
# baseline (speedup 1.0000x reference)
; #define PG8_STAGE(bufoff, gbase, voff) do { _Pragma("unroll") for (int _i = 0; _i < 2; ++_i) \
;         __builtin_amdgcn_global_load_lds((const __attribute__((address_space(1))) unsigned*)((const char*)(gbase) + (voff)[_i]), (LAS unsigned*)(lds + (bufoff) + ldsw + _i * 8192), 16, 0, 0); } while (0)
; #define PG8_WAIT_V(n) asm volatile("s_waitcnt vmcnt(" #n ")" ::: "memory")
; #define PG8_BAR __builtin_amdgcn_s_barrier()
; template <class Epi, class SchedT, bool ALIGN_EPI, bool SP2>
; __device__ __forceinline__ void gemm_phase(LAS unsigned char* lds, const int ldk, const int nt, const SchedT& S, const Epi& E) {
;     ...
;     for (int i = 0; i < 2; ++i) { int R, C; stage_rc(tid * 16 + i * 8192, R, C); const int Rb = 2 * (R & ~31) + perm32(R & 31);
;         voffA[i] = (unsigned)(R * K + C) * 2u; voffB[i] = (unsigned)(Rb * K + C) * 2u; }
;     const size_t kstep = (size_t)(BK * 2);
;     const size_t hstep = (size_t)HALF * K * 2;
;     const size_t hstepB = (size_t)32 * K * 2;
;     const unsigned ldsw = (unsigned)wid * 1024u;
;     const int aoff = lds_byte(wr * 64 + fr, fq * 8), boff = lds_byte(wc * 32 + fr, fq * 8);
;     ...
;     if constexpr (SP2) {
;         PG8_STAGE(PG8_SB(0, 0), cB, voffB); PG8_STAGE(PG8_SB(0, 1), cB + hstepB, voffB); PG8_STAGE(PG8_SA(0, 0), cA, voffA); PG8_STAGE(PG8_SA(0, 1), cA + hstep, voffA);
;         if (wr == 1) PG8_BAR;
;         PG8_WAIT_V(2); PG8_BAR;
;         PG8_STAGE(PG8_SB(1, 0), cB + kstep, voffB); PG8_STAGE(PG8_SA(1, 0), cA + kstep, voffA); PG8_STAGE(PG8_SB(1, 1), cB + hstepB + kstep, voffB);
;         PG8_WAIT_V(6); PG8_BAR;
.LBB0_112:
	s_mul_i32 s12, s16, 0x7500000
	v_writelane_b32 v163, s12, 36
	s_lshl_b32 s12, s16, 19
	s_mov_b32 s13, s23
	v_writelane_b32 v163, s12, 37
	s_mov_b32 s17, s23
	s_and_b64 vcc, exec, s[0:1]
	v_writelane_b32 v163, s13, 38
	v_writelane_b32 v163, s16, 39
	s_lshl_b64 s[0:1], s[16:17], 17
	s_nop 0
	v_writelane_b32 v163, s17, 40
	v_writelane_b32 v163, s0, 41
	s_nop 1
	v_writelane_b32 v163, s1, 42
	s_cbranch_vccnz .LBB0_358
	v_ashrrev_i32_e32 v3, 31, v0
	v_lshrrev_b32_e32 v3, 26, v3
	v_add_u32_e32 v3, v0, v3
	v_ashrrev_i32_e32 v10, 6, v3
	v_bfe_i32 v3, v0, 27, 1
	v_lshlrev_b32_e32 v2, 4, v0
	v_lshrrev_b32_e32 v3, 22, v3
	v_add_u32_e32 v3, v2, v3
	v_and_b32_e32 v3, 0xfffffc00, v3
	v_sub_u32_e32 v3, v2, v3
	v_lshrrev_b32_e32 v4, 4, v3
	v_bitop3_b32 v3, v4, v3, 32 bitop3:0x6c
	v_ashrrev_i32_e32 v5, 31, v3
	v_lshrrev_b32_e32 v5, 26, v5
	v_add_u32_e32 v5, v3, v5
	v_lshlrev_b32_e32 v4, 3, v10
	v_ashrrev_i32_e32 v11, 6, v5
	v_and_b32_e32 v5, 0xc0, v5
	v_and_b32_e32 v4, -16, v4
	v_sub_u32_e32 v3, v3, v5
	v_add_u32_e32 v4, v11, v4
	v_ashrrev_i16_sdwa v3, v244, sext(v3) dst_sel:DWORD dst_unused:UNUSED_PAD src0_sel:DWORD src1_sel:BYTE_0
	v_readlane_b32 s0, v163, 39
	v_lshlrev_b32_e32 v6, 5, v10
	v_bfe_i32 v12, v3, 0, 16
	v_lshlrev_b32_e32 v3, 1, v4
	v_lshrrev_b32_e32 v5, 2, v4
	s_mul_i32 s0, s0, 0x7500000
	v_and_b32_e32 v6, 32, v6
	v_and_b32_e32 v5, 4, v5
	v_and_b32_e32 v7, 3, v11
	v_and_b32_e32 v3, 0xfffd8, v3
	v_readlane_b32 s1, v163, 40
	s_add_u32 s0, s44, s0
	v_or3_b32 v3, v7, v5, v3
	v_add_lshl_u32 v5, v6, v12, 1
	v_add_u32_e32 v2, 0x2000, v2
	s_addc_u32 s1, s45, 0
	v_lshl_add_u32 v158, v3, 12, v5
	v_ashrrev_i32_e32 v3, 31, v2
	s_add_u32 s22, s0, 0x200000
	v_lshrrev_b32_e32 v3, 22, v3
	s_addc_u32 s84, s1, 0
	v_add_u32_e32 v3, v2, v3
	s_add_u32 s85, s44, 0xec00000
	v_ashrrev_i32_e32 v13, 10, v3
	s_addc_u32 s86, s45, 0
	s_ashr_i32 s0, s18, 6
	v_mul_i32_i24_e32 v3, 0x400, v13
	v_sub_u32_e32 v2, v2, v3
	s_ashr_i32 s94, s18, 8
	s_lshl_b32 s87, s0, 10
	v_lshrrev_b32_e32 v3, 4, v2
	s_cmp_eq_u32 s20, 0
	v_bitop3_b32 v2, v3, v2, 32 bitop3:0x6c
	s_cselect_b32 s12, s82, s51
	v_lshl_add_u32 v156, v4, 12, v5
	v_ashrrev_i32_e32 v4, 31, v2
	s_cselect_b32 s1, s86, s84
	s_cselect_b32 s17, s85, s22
	s_cselect_b32 s16, s51, s82
	s_cselect_b32 s19, s84, s86
	s_cselect_b32 s21, s22, s85
	s_ashr_i32 s13, s12, 31
	v_lshrrev_b32_e32 v4, 26, v4
	s_lshl_b64 s[12:13], s[12:13], 20
	v_add_u32_e32 v4, v2, v4
	s_add_u32 s12, s17, s12
	v_lshlrev_b32_e32 v3, 3, v13
	v_ashrrev_i32_e32 v14, 6, v4
	v_and_b32_e32 v4, 0xc0, v4
	s_addc_u32 s13, s1, s13
	s_ashr_i32 s17, s16, 31
	v_and_b32_e32 v3, -16, v3
	v_sub_u32_e32 v2, v2, v4
	s_lshl_b64 s[16:17], s[16:17], 20
	v_add_u32_e32 v3, v14, v3
	v_ashrrev_i16_sdwa v2, v244, sext(v2) dst_sel:DWORD dst_unused:UNUSED_PAD src0_sel:DWORD src1_sel:BYTE_0
	s_add_u32 s16, s21, s16
	v_lshlrev_b32_e32 v5, 5, v13
	v_bfe_i32 v15, v2, 0, 16
	v_lshlrev_b32_e32 v2, 1, v3
	v_lshrrev_b32_e32 v4, 2, v3
	s_addc_u32 s17, s19, s17
	s_add_i32 s88, s87, 0
	v_and_b32_e32 v5, 32, v5
	v_and_b32_e32 v4, 4, v4
	v_and_b32_e32 v6, 3, v14
	v_and_b32_e32 v2, 0xfffd8, v2
	s_add_i32 m0, s88, 0x10000
	v_or3_b32 v2, v6, v4, v2
	v_add_lshl_u32 v4, v5, v15, 1
	global_load_lds_dwordx4 v158, s[16:17]
	s_add_i32 m0, s88, 0x12000
	v_lshl_add_u32 v174, v2, 12, v4
	s_add_u32 s30, s16, 0x20000
	global_load_lds_dwordx4 v174, s[16:17]
	s_addc_u32 s31, s17, 0
	s_add_i32 m0, s88, 0x14000
	s_add_i32 s89, s88, 0x2000
	global_load_lds_dwordx4 v158, s[30:31]
	s_add_i32 m0, s88, 0x16000
	v_lshl_add_u32 v160, v3, 12, v4
	global_load_lds_dwordx4 v174, s[30:31]
	s_mov_b32 m0, s88
	s_add_u32 s30, s12, 0x80000
	global_load_lds_dwordx4 v156, s[12:13]
	s_mov_b32 m0, s89
	s_addc_u32 s31, s13, 0
	s_add_i32 s90, s88, 0x4000
	global_load_lds_dwordx4 v160, s[12:13]
	s_mov_b32 m0, s90
	s_add_i32 s91, s88, 0x6000
	global_load_lds_dwordx4 v156, s[30:31]
	s_mov_b32 m0, s91
	v_mov_b32_e32 v159, v1
	global_load_lds_dwordx4 v160, s[30:31]
	v_mov_b32_e32 v175, v1
	v_mov_b32_e32 v157, v1
	v_mov_b32_e32 v161, v1
	s_cmp_eq_u32 s94, 1
	v_lshl_add_u64 v[8:9], s[16:17], 0, v[158:159]
	v_lshl_add_u64 v[6:7], s[16:17], 0, v[174:175]
	v_lshl_add_u64 v[2:3], s[12:13], 0, v[156:157]
	s_cselect_b64 s[46:47], -1, 0
	v_lshl_add_u64 v[4:5], s[12:13], 0, v[160:161]
	v_readlane_b32 s30, v163, 37
	v_readlane_b32 s31, v163, 38
	s_lshl_b64 s[30:31], s[30:31], 2
	s_add_u32 s1, s44, s30
	s_addc_u32 s19, s45, s31
	s_add_u32 s30, s1, 0x27c00000
	s_addc_u32 s31, s19, 0
	s_add_u32 s48, s44, 0x16c00000
	s_addc_u32 s49, s45, 0
	s_add_u32 s74, s44, 0x17c00000
	s_addc_u32 s75, s45, 0
	s_add_u32 s34, s44, 0x18c00000
	s_addc_u32 s35, s45, 0
	v_writelane_b32 v163, s34, 43
	s_add_u32 s54, s44, 0x1bc00000
	s_addc_u32 s55, s45, 0
	v_writelane_b32 v163, s35, 44
	v_lshl_add_u64 v[8:9], v[8:9], 0, s[24:25]
	v_readlane_b32 s34, v163, 41
	v_readlane_b32 s35, v163, 42
	s_lshl_b64 s[34:35], s[34:35], 2
	s_add_u32 s1, s44, s34
	s_addc_u32 s19, s45, s35
	s_add_u32 s56, s1, 0x28100000
	s_addc_u32 s57, s19, 0
	s_and_b32 s19, s0, 3
	s_add_i32 m0, s88, 0x18000
	s_lshl_b32 s21, s94, 13
	s_lshl_b32 s34, s19, 12
	global_load_lds_dwordx4 v[8:9], off
	v_lshl_add_u64 v[6:7], v[6:7], 0, s[24:25]
	s_add_i32 m0, s88, 0x1a000
	s_add_i32 s92, s88, 0x8000
	s_add_i32 s93, s88, 0xa000
	global_load_lds_dwordx4 v[6:7], off
	v_lshl_add_u64 v[2:3], v[2:3], 0, s[24:25]
	s_mov_b32 m0, s92
	s_add_u32 s0, s16, 0x20080
	global_load_lds_dwordx4 v[2:3], off
	v_lshl_add_u64 v[2:3], v[4:5], 0, s[24:25]
	s_mov_b32 m0, s93
	s_addc_u32 s1, s17, 0
	global_load_lds_dwordx4 v[2:3], off
	s_add_i32 m0, s88, 0x1c000
	v_lshl_add_u64 v[2:3], s[0:1], 0, v[158:159]
	global_load_lds_dwordx4 v[2:3], off
	v_lshl_add_u64 v[2:3], s[0:1], 0, v[174:175]
	s_add_i32 m0, s88, 0x1e000
	v_and_b32_e32 v210, 15, v0
	global_load_lds_dwordx4 v[2:3], off
	s_cmp_lg_u32 s94, 1
	s_cbranch_scc1 .LBB0_115
	s_barrier
; #define PG8_STAGE(bufoff, gbase, voff) do { _Pragma("unroll") for (int _i = 0; _i < 2; ++_i) \
;         __builtin_amdgcn_global_load_lds((const __attribute__((address_space(1))) unsigned*)((const char*)(gbase) + (voff)[_i]), (LAS unsigned*)(lds + (bufoff) + ldsw + _i * 8192), 16, 0, 0); } while (0)
; #define PG8_WAIT_V(n) asm volatile("s_waitcnt vmcnt(" #n ")" ::: "memory")
; #define PG8_BAR __builtin_amdgcn_s_barrier()
; template <class Epi, class SchedT, bool ALIGN_EPI, bool SP2>
; __device__ __forceinline__ void gemm_phase(LAS unsigned char* lds, const int ldk, const int nt, const SchedT& S, const Epi& E) {
;     ...
;     if constexpr (SP2) {
;         PG8_STAGE(PG8_SB(0, 0), cB, voffB); PG8_STAGE(PG8_SB(0, 1), cB + hstepB, voffB); PG8_STAGE(PG8_SA(0, 0), cA, voffA); PG8_STAGE(PG8_SA(0, 1), cA + hstep, voffA);
;         if (wr == 1) PG8_BAR;
;         PG8_WAIT_V(2); PG8_BAR;
;         PG8_STAGE(PG8_SB(1, 0), cB + kstep, voffB); PG8_STAGE(PG8_SA(1, 0), cA + kstep, voffA); PG8_STAGE(PG8_SB(1, 1), cB + hstepB + kstep, voffB);
;         PG8_WAIT_V(6); PG8_BAR;
.LBB0_115:
	s_waitcnt vmcnt(8)
	s_barrier
	v_bfe_u32 v2, v0, 4, 2
	v_lshlrev_b32_e32 v5, 2, v0
	v_and_b32_e32 v213, 7, v0
	v_lshlrev_b32_e32 v0, 3, v0
	v_and_b32_e32 v0, 64, v0
	v_lshl_add_u64 v[176:177], s[30:31], 0, v[0:1]
	v_lshlrev_b32_e32 v0, 5, v2
	v_lshl_add_u64 v[178:179], s[30:31], 0, v[0:1]
	v_lshlrev_b32_e32 v0, 15, v10
	v_and_b32_e32 v0, 0xffff0000, v0
	v_lshlrev_b32_e32 v3, 3, v2
	v_lshlrev_b32_e32 v4, 4, v2
	v_lshlrev_b32_e32 v214, 6, v2
	v_lshl_add_u32 v0, v11, 12, v0
	v_and_b32_e32 v2, 1, v10
	v_lshl_or_b32 v0, v2, 6, v0
	v_lshl_add_u32 v180, v12, 1, v0
	v_lshlrev_b32_e32 v0, 15, v13
	v_and_b32_e32 v0, 0xffff0000, v0
	v_lshl_or_b32 v4, v210, 6, v4
	v_and_b32_e32 v5, 32, v5
	s_waitcnt vmcnt(6)
	v_lshl_add_u32 v0, v14, 12, v0
	v_and_b32_e32 v2, 1, v13
	v_bitop3_b32 v6, v4, s21, v5 bitop3:0xde
	s_cmpk_lt_u32 s18, 0x100
	v_lshl_or_b32 v0, v2, 6, v0
	v_lshl_or_b32 v211, s94, 6, v210
	v_bitop3_b32 v212, v4, s34, v5 bitop3:0xde
	s_cselect_b64 s[58:59], -1, 0
	s_add_i32 s94, s94, -8
	v_lshl_or_b32 v215, s19, 6, v3
	v_mov_b32_e32 v181, v1
	v_lshl_add_u32 v182, v15, 1, v0
	v_mov_b32_e32 v183, v1
	s_mov_b32 s95, 0
	v_add_u32_e32 v216, 0, v6
	s_mov_b32 s64, 0x503ce6da
	s_barrier
	s_branch .LBB0_118

; #define PG8_STAGE(bufoff, gbase, voff) do { _Pragma("unroll") for (int _i = 0; _i < 2; ++_i) \
;         __builtin_amdgcn_global_load_lds((const __attribute__((address_space(1))) unsigned*)((const char*)(gbase) + (voff)[_i]), (LAS unsigned*)(lds + (bufoff) + ldsw + _i * 8192), 16, 0, 0); } while (0)
; #define PG8_WAIT_V(n) asm volatile("s_waitcnt vmcnt(" #n ")" ::: "memory")
; #define PG8_BAR __builtin_amdgcn_s_barrier()
; template <class Epi, class SchedT, bool ALIGN_EPI, bool SP2>
; __device__ __forceinline__ void gemm_phase(LAS unsigned char* lds, const int ldk, const int nt, const SchedT& S, const Epi& E) {
;     ...
;     for (int i = 0; i < 2; ++i) { int R, C; stage_rc(tid * 16 + i * 8192, R, C); const int Rb = 2 * (R & ~31) + perm32(R & 31);
;         voffA[i] = (unsigned)(R * K + C) * 2u; voffB[i] = (unsigned)(Rb * K + C) * 2u; }
;     const size_t kstep = (size_t)(BK * 2);
;     const size_t hstep = (size_t)HALF * K * 2;
;     const size_t hstepB = (size_t)32 * K * 2;
;     const unsigned ldsw = (unsigned)wid * 1024u;
;     const int aoff = lds_byte(wr * 64 + fr, fq * 8), boff = lds_byte(wc * 32 + fr, fq * 8);
;     ...
;     if constexpr (SP2) {
;         PG8_STAGE(PG8_SB(0, 0), cB, voffB); PG8_STAGE(PG8_SB(0, 1), cB + hstepB, voffB); PG8_STAGE(PG8_SA(0, 0), cA, voffA); PG8_STAGE(PG8_SA(0, 1), cA + hstep, voffA);
;         if (wr == 1) PG8_BAR;
;         PG8_WAIT_V(2); PG8_BAR;
;         PG8_STAGE(PG8_SB(1, 0), cB + kstep, voffB); PG8_STAGE(PG8_SA(1, 0), cA + kstep, voffA); PG8_STAGE(PG8_SB(1, 1), cB + hstepB + kstep, voffB);
;         PG8_WAIT_V(6); PG8_BAR;
.LBB0_523:
	v_readlane_b32 s18, v163, 43
	v_readlane_b32 s19, v163, 44
	s_and_b64 vcc, exec, s[18:19]
	s_cbranch_vccnz .LBB0_607
	v_ashrrev_i32_e32 v3, 31, v0
	v_lshrrev_b32_e32 v3, 26, v3
	v_add_u32_e32 v3, v0, v3
	v_ashrrev_i32_e32 v10, 6, v3
	v_bfe_i32 v3, v0, 27, 1
	v_lshlrev_b32_e32 v2, 4, v0
	v_lshrrev_b32_e32 v3, 22, v3
	v_add_u32_e32 v3, v2, v3
	v_and_b32_e32 v3, 0xfffffc00, v3
	v_sub_u32_e32 v3, v2, v3
	v_lshrrev_b32_e32 v4, 4, v3
	v_bitop3_b32 v3, v4, v3, 32 bitop3:0x6c
	v_ashrrev_i32_e32 v5, 31, v3
	v_lshrrev_b32_e32 v5, 26, v5
	v_add_u32_e32 v5, v3, v5
	v_lshlrev_b32_e32 v4, 3, v10
	v_ashrrev_i32_e32 v11, 6, v5
	v_and_b32_e32 v5, 0xc0, v5
	v_and_b32_e32 v4, -16, v4
	v_sub_u32_e32 v3, v3, v5
	v_add_u32_e32 v4, v11, v4
	v_ashrrev_i16_sdwa v3, v244, sext(v3) dst_sel:DWORD dst_unused:UNUSED_PAD src0_sel:DWORD src1_sel:BYTE_0
	v_lshlrev_b32_e32 v6, 5, v10
	v_bfe_i32 v12, v3, 0, 16
	v_lshlrev_b32_e32 v3, 1, v4
	v_lshrrev_b32_e32 v5, 2, v4
	v_and_b32_e32 v6, 32, v6
	v_and_b32_e32 v5, 4, v5
	v_and_b32_e32 v7, 3, v11
	v_and_b32_e32 v3, 0xfffd8, v3
	v_or3_b32 v3, v7, v5, v3
	v_add_lshl_u32 v5, v6, v12, 1
	v_add_u32_e32 v2, 0x2000, v2
	v_lshl_add_u32 v134, v3, 12, v5
	v_ashrrev_i32_e32 v3, 31, v2
	v_lshrrev_b32_e32 v3, 22, v3
	v_add_u32_e32 v3, v2, v3
	v_ashrrev_i32_e32 v13, 10, v3
	v_readlane_b32 s18, v163, 39
	v_mul_i32_i24_e32 v3, 0x400, v13
	s_mul_i32 s13, s18, 0x7500000
	v_sub_u32_e32 v2, v2, v3
	s_add_u32 s13, s0, s13
	v_lshrrev_b32_e32 v3, 4, v2
	s_addc_u32 s17, s1, 0
	v_bitop3_b32 v2, v3, v2, 32 bitop3:0x6c
	s_add_u32 s21, s0, 0x1fc00000
	v_lshl_add_u32 v132, v4, 12, v5
	v_ashrrev_i32_e32 v4, 31, v2
	s_addc_u32 s22, s1, 0
	v_lshrrev_b32_e32 v4, 26, v4
	s_add_u32 s54, s13, 0x2600000
	v_add_u32_e32 v4, v2, v4
	v_readlane_b32 s19, v163, 40
	s_addc_u32 s55, s17, 0
	s_ashr_i32 s38, s20, 6
	v_lshlrev_b32_e32 v3, 3, v13
	v_ashrrev_i32_e32 v14, 6, v4
	v_and_b32_e32 v4, 0xc0, v4
	s_ashr_i32 s17, s16, 31
	s_ashr_i32 s13, s12, 31
	v_and_b32_e32 v3, -16, v3
	v_sub_u32_e32 v2, v2, v4
	s_ashr_i32 s39, s20, 8
	s_lshl_b32 s56, s38, 10
	s_lshl_b64 s[18:19], s[16:17], 20
	s_lshl_b64 s[30:31], s[12:13], 20
	v_add_u32_e32 v3, v14, v3
	v_ashrrev_i16_sdwa v2, v244, sext(v2) dst_sel:DWORD dst_unused:UNUSED_PAD src0_sel:DWORD src1_sel:BYTE_0
	s_add_u32 s36, s54, s30
	v_lshlrev_b32_e32 v5, 5, v13
	v_bfe_i32 v15, v2, 0, 16
	v_lshlrev_b32_e32 v2, 1, v3
	v_lshrrev_b32_e32 v4, 2, v3
	s_addc_u32 s37, s55, s31
	s_add_i32 s57, s56, 0
	v_and_b32_e32 v5, 32, v5
	v_and_b32_e32 v4, 4, v4
	v_and_b32_e32 v6, 3, v14
	v_and_b32_e32 v2, 0xfffd8, v2
	s_add_i32 m0, s57, 0x10000
	v_or3_b32 v2, v6, v4, v2
	v_add_lshl_u32 v4, v5, v15, 1
	global_load_lds_dwordx4 v134, s[36:37]
	s_add_i32 m0, s57, 0x12000
	v_lshl_add_u32 v138, v2, 12, v4
	s_add_u32 s30, s36, 0x20000
	global_load_lds_dwordx4 v138, s[36:37]
	s_addc_u32 s31, s37, 0
	s_add_i32 m0, s57, 0x14000
	v_lshl_add_u32 v136, v3, 12, v4
	global_load_lds_dwordx4 v134, s[30:31]
	s_add_i32 m0, s57, 0x16000
	s_add_u32 s34, s21, s18
	s_addc_u32 s35, s22, s19
	s_add_i32 s58, s57, 0x2000
	global_load_lds_dwordx4 v138, s[30:31]
	s_mov_b32 m0, s57
	s_add_u32 s18, s34, 0x80000
	global_load_lds_dwordx4 v132, s[34:35]
	s_mov_b32 m0, s58
	s_addc_u32 s19, s35, 0
	s_add_i32 s59, s57, 0x4000
	global_load_lds_dwordx4 v136, s[34:35]
	s_mov_b32 m0, s59
	s_add_i32 s60, s57, 0x6000
	global_load_lds_dwordx4 v132, s[18:19]
	s_mov_b32 m0, s60
	v_mov_b32_e32 v135, v1
	global_load_lds_dwordx4 v136, s[18:19]
	v_mov_b32_e32 v139, v1
	v_mov_b32_e32 v133, v1
	v_mov_b32_e32 v137, v1
	s_cmp_eq_u32 s39, 1
	v_lshl_add_u64 v[8:9], s[36:37], 0, v[134:135]
	v_lshl_add_u64 v[6:7], s[36:37], 0, v[138:139]
	v_lshl_add_u64 v[2:3], s[34:35], 0, v[132:133]
	s_cselect_b64 s[18:19], -1, 0
	v_lshl_add_u64 v[4:5], s[34:35], 0, v[136:137]
	s_add_u32 s30, s0, 0x1bc00000
	s_addc_u32 s31, s1, 0
	s_add_u32 s42, s0, 0x25c00000
	s_addc_u32 s43, s1, 0
	s_and_b32 s13, s38, 3
	s_add_i32 m0, s57, 0x18000
	v_lshl_add_u64 v[8:9], v[8:9], 0, s[24:25]
	s_lshl_b32 s17, s39, 13
	s_lshl_b32 s38, s13, 12
	global_load_lds_dwordx4 v[8:9], off
	v_lshl_add_u64 v[6:7], v[6:7], 0, s[24:25]
	s_add_i32 m0, s57, 0x1a000
	s_add_i32 s61, s57, 0x8000
	s_add_i32 s62, s57, 0xa000
	global_load_lds_dwordx4 v[6:7], off
	v_lshl_add_u64 v[2:3], v[2:3], 0, s[24:25]
	s_mov_b32 m0, s61
	s_add_u32 s0, s36, 0x20080
	global_load_lds_dwordx4 v[2:3], off
	v_lshl_add_u64 v[2:3], v[4:5], 0, s[24:25]
	s_mov_b32 m0, s62
	s_addc_u32 s1, s37, 0
	global_load_lds_dwordx4 v[2:3], off
	s_add_i32 m0, s57, 0x1c000
	v_lshl_add_u64 v[2:3], s[0:1], 0, v[134:135]
	global_load_lds_dwordx4 v[2:3], off
	v_lshl_add_u64 v[2:3], s[0:1], 0, v[138:139]
	s_add_i32 m0, s57, 0x1e000
	s_cmpk_lt_u32 s20, 0x100
	global_load_lds_dwordx4 v[2:3], off
	s_cmp_lg_u32 s39, 1
	s_cbranch_scc1 .LBB0_526
	s_barrier
; #define PG8_STAGE(bufoff, gbase, voff) do { _Pragma("unroll") for (int _i = 0; _i < 2; ++_i) \
;         __builtin_amdgcn_global_load_lds((const __attribute__((address_space(1))) unsigned*)((const char*)(gbase) + (voff)[_i]), (LAS unsigned*)(lds + (bufoff) + ldsw + _i * 8192), 16, 0, 0); } while (0)
; #define PG8_WAIT_V(n) asm volatile("s_waitcnt vmcnt(" #n ")" ::: "memory")
; #define PG8_BAR __builtin_amdgcn_s_barrier()
; template <class Epi, class SchedT, bool ALIGN_EPI, bool SP2>
; __device__ __forceinline__ void gemm_phase(LAS unsigned char* lds, const int ldk, const int nt, const SchedT& S, const Epi& E) {
;     ...
;     f32x4 acc[2][2][4][2];
; #pragma unroll
;     for (int a = 0; a < 2; ++a)
; #pragma unroll
;         for (int b = 0; b < 2; ++b)
; #pragma unroll
;             for (int m = 0; m < 4; ++m)
; #pragma unroll
;                 for (int n = 0; n < 2; ++n) acc[a][b][m][n] = (f32x4){0.f, 0.f, 0.f, 0.f};
;     bf16x8 At[4][2], B0[2][2], B1[2][2];
;     const char* cA; const char* cB; S.ptrs(cur, cA, cB);
;     if constexpr (SP2) {
;         PG8_STAGE(PG8_SB(0, 0), cB, voffB); PG8_STAGE(PG8_SB(0, 1), cB + hstepB, voffB); PG8_STAGE(PG8_SA(0, 0), cA, voffA); PG8_STAGE(PG8_SA(0, 1), cA + hstep, voffA);
;         if (wr == 1) PG8_BAR;
;         PG8_WAIT_V(2); PG8_BAR;
;         PG8_STAGE(PG8_SB(1, 0), cB + kstep, voffB); PG8_STAGE(PG8_SA(1, 0), cA + kstep, voffA); PG8_STAGE(PG8_SB(1, 1), cB + hstepB + kstep, voffB);
;         PG8_WAIT_V(6); PG8_BAR;
.LBB0_526:
	s_waitcnt vmcnt(8)
	s_barrier
	v_lshrrev_b32_e32 v3, 1, v0
	v_and_b32_e32 v3, 24, v3
	v_and_b32_e32 v2, 15, v0
	v_lshlrev_b32_e32 v4, 1, v3
	v_lshlrev_b32_e32 v0, 2, v0
	v_lshl_or_b32 v158, s39, 6, v2
	v_lshl_or_b32 v2, v2, 6, v4
	v_and_b32_e32 v0, 32, v0
	v_bitop3_b32 v4, v2, s17, v0 bitop3:0xde
	v_bitop3_b32 v159, v2, s38, v0 bitop3:0xde
	v_lshlrev_b32_e32 v0, 15, v10
	v_and_b32_e32 v0, 0xffff0000, v0
	v_lshl_add_u32 v0, v11, 12, v0
	v_and_b32_e32 v2, 1, v10
	v_lshl_or_b32 v0, v2, 6, v0
	v_lshl_add_u32 v140, v12, 1, v0
	v_lshlrev_b32_e32 v0, 15, v13
	v_and_b32_e32 v0, 0xffff0000, v0
	v_lshl_add_u32 v0, v14, 12, v0
	v_and_b32_e32 v2, 1, v13
	s_waitcnt vmcnt(6)
	v_lshl_or_b32 v160, s13, 6, v3
	v_lshl_or_b32 v0, v2, 6, v0
	v_mov_b32_e32 v2, v1
	v_mov_b32_e32 v3, v1
	v_lshl_add_u32 v142, v15, 1, v0
	v_mov_b32_e32 v0, v1
	v_add_u32_e32 v161, 0, v4
	v_mov_b64_e32 v[6:7], v[2:3]
	v_mov_b64_e32 v[10:11], v[2:3]
	v_mov_b64_e32 v[14:15], v[2:3]
	v_mov_b64_e32 v[18:19], v[2:3]
	v_mov_b64_e32 v[22:23], v[2:3]
	v_mov_b64_e32 v[26:27], v[2:3]
	v_mov_b64_e32 v[30:31], v[2:3]
	v_mov_b64_e32 v[34:35], v[2:3]
	v_mov_b64_e32 v[38:39], v[2:3]
	v_mov_b64_e32 v[42:43], v[2:3]
	v_mov_b64_e32 v[46:47], v[2:3]
	v_mov_b64_e32 v[50:51], v[2:3]
	v_mov_b64_e32 v[54:55], v[2:3]
	v_mov_b64_e32 v[58:59], v[2:3]
	v_mov_b64_e32 v[62:63], v[2:3]
	v_mov_b64_e32 v[66:67], v[2:3]
	v_mov_b64_e32 v[70:71], v[2:3]
	v_mov_b64_e32 v[74:75], v[2:3]
	v_mov_b64_e32 v[78:79], v[2:3]
	v_mov_b64_e32 v[82:83], v[2:3]
	v_mov_b64_e32 v[86:87], v[2:3]
	v_mov_b64_e32 v[90:91], v[2:3]
	v_mov_b64_e32 v[94:95], v[2:3]
	v_mov_b64_e32 v[98:99], v[2:3]
	v_mov_b64_e32 v[102:103], v[2:3]
	v_mov_b64_e32 v[106:107], v[2:3]
	v_mov_b64_e32 v[110:111], v[2:3]
	v_mov_b64_e32 v[114:115], v[2:3]
	v_mov_b64_e32 v[118:119], v[2:3]
	v_mov_b64_e32 v[122:123], v[2:3]
	v_mov_b64_e32 v[126:127], v[2:3]
	v_mov_b64_e32 v[130:131], v[2:3]
	s_cselect_b64 s[44:45], -1, 0
	v_mov_b32_e32 v141, v1
	v_mov_b32_e32 v143, v1
	s_mov_b32 s13, 0
	v_mov_b64_e32 v[4:5], v[0:1]
	v_mov_b64_e32 v[8:9], v[0:1]
	v_mov_b64_e32 v[12:13], v[0:1]
	v_mov_b64_e32 v[16:17], v[0:1]
	v_mov_b64_e32 v[20:21], v[0:1]
	v_mov_b64_e32 v[24:25], v[0:1]
	v_mov_b64_e32 v[28:29], v[0:1]
	v_mov_b64_e32 v[32:33], v[0:1]
	v_mov_b64_e32 v[36:37], v[0:1]
	v_mov_b64_e32 v[40:41], v[0:1]
	v_mov_b64_e32 v[44:45], v[0:1]
	v_mov_b64_e32 v[48:49], v[0:1]
	v_mov_b64_e32 v[52:53], v[0:1]
	v_mov_b64_e32 v[56:57], v[0:1]
	v_mov_b64_e32 v[60:61], v[0:1]
	v_mov_b64_e32 v[64:65], v[0:1]
	v_mov_b64_e32 v[68:69], v[0:1]
	v_mov_b64_e32 v[72:73], v[0:1]
	v_mov_b64_e32 v[76:77], v[0:1]
	v_mov_b64_e32 v[80:81], v[0:1]
	v_mov_b64_e32 v[84:85], v[0:1]
	v_mov_b64_e32 v[88:89], v[0:1]
	v_mov_b64_e32 v[92:93], v[0:1]
	v_mov_b64_e32 v[96:97], v[0:1]
	v_mov_b64_e32 v[100:101], v[0:1]
	v_mov_b64_e32 v[104:105], v[0:1]
	v_mov_b64_e32 v[108:109], v[0:1]
	v_mov_b64_e32 v[112:113], v[0:1]
	v_mov_b64_e32 v[116:117], v[0:1]
	v_mov_b64_e32 v[120:121], v[0:1]
	v_mov_b64_e32 v[124:125], v[0:1]
	v_mov_b64_e32 v[128:129], v[0:1]
	s_mov_b32 s63, 0
	s_barrier
	s_branch .LBB0_529

; #define PG8_STAGE(bufoff, gbase, voff) do { _Pragma("unroll") for (int _i = 0; _i < 2; ++_i) \
;         __builtin_amdgcn_global_load_lds((const __attribute__((address_space(1))) unsigned*)((const char*)(gbase) + (voff)[_i]), (LAS unsigned*)(lds + (bufoff) + ldsw + _i * 8192), 16, 0, 0); } while (0)
; #define PG8_WAIT_V(n) asm volatile("s_waitcnt vmcnt(" #n ")" ::: "memory")
; #define PG8_BAR __builtin_amdgcn_s_barrier()
; template <class Epi, class SchedT, bool ALIGN_EPI, bool SP2>
; __device__ __forceinline__ void gemm_phase(LAS unsigned char* lds, const int ldk, const int nt, const SchedT& S, const Epi& E) {
;     ...
;     for (int i = 0; i < 2; ++i) { int R, C; stage_rc(tid * 16 + i * 8192, R, C); const int Rb = 2 * (R & ~31) + perm32(R & 31);
;         voffA[i] = (unsigned)(R * K + C) * 2u; voffB[i] = (unsigned)(Rb * K + C) * 2u; }
;     const size_t kstep = (size_t)(BK * 2);
;     const size_t hstep = (size_t)HALF * K * 2;
;     const size_t hstepB = (size_t)32 * K * 2;
;     const unsigned ldsw = (unsigned)wid * 1024u;
;     const int aoff = lds_byte(wr * 64 + fr, fq * 8), boff = lds_byte(wc * 32 + fr, fq * 8);
;     ...
;     if constexpr (SP2) {
;         PG8_STAGE(PG8_SB(0, 0), cB, voffB); PG8_STAGE(PG8_SB(0, 1), cB + hstepB, voffB); PG8_STAGE(PG8_SA(0, 0), cA, voffA); PG8_STAGE(PG8_SA(0, 1), cA + hstep, voffA);
;         if (wr == 1) PG8_BAR;
;         PG8_WAIT_V(2); PG8_BAR;
;         PG8_STAGE(PG8_SB(1, 0), cB + kstep, voffB); PG8_STAGE(PG8_SA(1, 0), cA + kstep, voffA); PG8_STAGE(PG8_SB(1, 1), cB + hstepB + kstep, voffB);
;         PG8_WAIT_V(6); PG8_BAR;
.LBB0_657:
	v_readlane_b32 s18, v163, 37
	v_readlane_b32 s19, v163, 38
	s_or_b32 s30, s18, 0x40000
	v_readlane_b32 s18, v163, 43
	v_readlane_b32 s19, v163, 44
	s_and_b64 vcc, exec, s[18:19]
	s_mov_b32 s31, s23
	s_cbranch_vccnz .LBB0_691
	v_ashrrev_i32_e32 v0, 31, v16
	v_lshrrev_b32_e32 v0, 26, v0
	v_add_u32_e32 v0, v16, v0
	v_ashrrev_i32_e32 v10, 6, v0
	v_bfe_i32 v0, v16, 27, 1
	v_lshlrev_b32_e32 v2, 4, v16
	v_lshrrev_b32_e32 v0, 22, v0
	v_add_u32_e32 v0, v2, v0
	v_and_b32_e32 v0, 0xfffffc00, v0
	v_sub_u32_e32 v0, v2, v0
	v_lshrrev_b32_e32 v3, 4, v0
	v_bitop3_b32 v0, v3, v0, 32 bitop3:0x6c
	v_ashrrev_i32_e32 v4, 31, v0
	v_lshrrev_b32_e32 v4, 26, v4
	v_add_u32_e32 v4, v0, v4
	v_lshlrev_b32_e32 v3, 3, v10
	v_ashrrev_i32_e32 v11, 6, v4
	v_and_b32_e32 v4, 0xc0, v4
	v_and_b32_e32 v3, -16, v3
	v_sub_u32_e32 v0, v0, v4
	v_add_u32_e32 v3, v11, v3
	v_ashrrev_i16_sdwa v0, v244, sext(v0) dst_sel:DWORD dst_unused:UNUSED_PAD src0_sel:DWORD src1_sel:BYTE_0
	v_lshlrev_b32_e32 v5, 5, v10
	v_bfe_i32 v12, v0, 0, 16
	v_lshlrev_b32_e32 v0, 1, v3
	v_lshrrev_b32_e32 v4, 2, v3
	v_and_b32_e32 v5, 32, v5
	v_and_b32_e32 v4, 4, v4
	v_and_b32_e32 v6, 3, v11
	v_and_b32_e32 v0, 0xfffd8, v0
	v_or3_b32 v0, v6, v4, v0
	v_add_lshl_u32 v4, v5, v12, 1
	v_add_u32_e32 v2, 0x2000, v2
	v_lshl_add_u32 v130, v3, 12, v4
	v_ashrrev_i32_e32 v3, 31, v2
	v_lshrrev_b32_e32 v3, 22, v3
	v_add_u32_e32 v3, v2, v3
	v_ashrrev_i32_e32 v13, 10, v3
	v_readlane_b32 s18, v163, 39
	v_mul_i32_i24_e32 v3, 0x400, v13
	s_mul_i32 s13, s18, 0x7500000
	v_sub_u32_e32 v2, v2, v3
	s_add_u32 s13, s0, s13
	v_lshrrev_b32_e32 v3, 4, v2
	s_addc_u32 s17, s1, 0
	v_bitop3_b32 v2, v3, v2, 32 bitop3:0x6c
	s_add_u32 s21, s0, 0x25c00000
	v_lshl_add_u32 v0, v0, 12, v4
	v_ashrrev_i32_e32 v4, 31, v2
	s_addc_u32 s58, s1, 0
	v_lshrrev_b32_e32 v4, 26, v4
	s_add_u32 s59, s13, 0x2e00000
	v_add_u32_e32 v4, v2, v4
	v_readlane_b32 s19, v163, 40
	s_addc_u32 s60, s17, 0
	s_ashr_i32 s22, s20, 6
	v_lshlrev_b32_e32 v3, 3, v13
	v_ashrrev_i32_e32 v14, 6, v4
	v_and_b32_e32 v4, 0xc0, v4
	s_ashr_i32 s17, s16, 31
	s_ashr_i32 s13, s12, 31
	v_and_b32_e32 v3, -16, v3
	v_sub_u32_e32 v2, v2, v4
	s_ashr_i32 s38, s20, 8
	s_lshl_b32 s61, s22, 10
	s_lshl_b64 s[18:19], s[16:17], 20
	s_lshl_b64 s[34:35], s[12:13], 20
	v_add_u32_e32 v3, v14, v3
	v_ashrrev_i16_sdwa v2, v244, sext(v2) dst_sel:DWORD dst_unused:UNUSED_PAD src0_sel:DWORD src1_sel:BYTE_0
	s_add_u32 s36, s59, s34
	v_lshlrev_b32_e32 v5, 5, v13
	v_bfe_i32 v15, v2, 0, 16
	v_lshlrev_b32_e32 v2, 1, v3
	v_lshrrev_b32_e32 v4, 2, v3
	s_addc_u32 s37, s60, s35
	s_add_i32 s17, s61, 0
	v_and_b32_e32 v5, 32, v5
	v_and_b32_e32 v4, 4, v4
	v_and_b32_e32 v6, 3, v14
	v_and_b32_e32 v2, 0xfffd8, v2
	s_add_i32 m0, s17, 0x10000
	v_or3_b32 v2, v6, v4, v2
	v_add_lshl_u32 v4, v5, v15, 1
	global_load_lds_dwordx4 v0, s[36:37]
	s_add_i32 m0, s17, 0x12000
	v_lshl_add_u32 v134, v2, 12, v4
	s_add_u32 s34, s36, 0x20000
	global_load_lds_dwordx4 v134, s[36:37]
	s_addc_u32 s35, s37, 0
	s_add_i32 m0, s17, 0x14000
	v_lshl_add_u32 v132, v3, 12, v4
	global_load_lds_dwordx4 v0, s[34:35]
	s_add_i32 m0, s17, 0x16000
	v_mov_b32_e32 v135, v1
	global_load_lds_dwordx4 v134, s[34:35]
	s_add_u32 s34, s21, s18
	s_addc_u32 s35, s58, s19
	s_add_i32 s62, s17, 0x2000
	s_mov_b32 m0, s17
	s_add_u32 s18, s34, 0x80000
	global_load_lds_dwordx4 v130, s[34:35]
	s_mov_b32 m0, s62
	s_addc_u32 s19, s35, 0
	s_add_i32 s63, s17, 0x4000
	global_load_lds_dwordx4 v132, s[34:35]
	s_mov_b32 m0, s63
	s_add_i32 s81, s17, 0x6000
	global_load_lds_dwordx4 v130, s[18:19]
	s_mov_b32 m0, s81
	v_mov_b32_e32 v131, v1
	global_load_lds_dwordx4 v132, s[18:19]
	v_mov_b32_e32 v133, v1
	s_cmp_eq_u32 s38, 1
	v_lshl_add_u64 v[8:9], s[36:37], 0, v[0:1]
	v_lshl_add_u64 v[6:7], s[36:37], 0, v[134:135]
	v_lshl_add_u64 v[2:3], s[34:35], 0, v[130:131]
	s_cselect_b64 s[18:19], -1, 0
	v_lshl_add_u64 v[4:5], s[34:35], 0, v[132:133]
	s_add_u32 s42, s0, 0xec00000
	s_addc_u32 s43, s1, 0
	s_add_u32 s44, s0, 0x10c00000
	s_addc_u32 s45, s1, 0
	s_lshl_b64 s[40:41], s[30:31], 2
	s_add_u32 s0, s0, s40
	s_addc_u32 s1, s1, s41
	v_bfe_u32 v18, v16, 4, 2
	s_add_u32 s46, s0, 0x27c00000
	v_and_b32_e32 v17, 15, v16
	v_lshlrev_b32_e32 v20, 4, v18
	v_lshlrev_b32_e32 v16, 2, v16
	s_addc_u32 s47, s1, 0
	s_and_b32 s82, s22, 3
	v_lshl_or_b32 v146, s38, 6, v17
	v_lshl_or_b32 v17, v17, 6, v20
	s_lshl_b32 s0, s38, 13
	v_and_b32_e32 v16, 32, v16
	s_add_i32 m0, s17, 0x18000
	v_lshl_add_u64 v[8:9], v[8:9], 0, s[24:25]
	v_bitop3_b32 v20, v17, s0, v16 bitop3:0xde
	s_lshl_b32 s0, s82, 12
	global_load_lds_dwordx4 v[8:9], off
	v_lshl_add_u64 v[6:7], v[6:7], 0, s[24:25]
	s_add_i32 m0, s17, 0x1a000
	s_add_i32 s83, s17, 0x8000
	s_add_i32 s84, s17, 0xa000
	v_bitop3_b32 v147, v17, s0, v16 bitop3:0xde
	global_load_lds_dwordx4 v[6:7], off
	v_lshl_add_u64 v[2:3], v[2:3], 0, s[24:25]
	s_mov_b32 m0, s83
	s_add_u32 s0, s36, 0x20080
	global_load_lds_dwordx4 v[2:3], off
	v_lshl_add_u64 v[2:3], v[4:5], 0, s[24:25]
	s_mov_b32 m0, s84
	s_addc_u32 s1, s37, 0
	global_load_lds_dwordx4 v[2:3], off
	s_add_i32 m0, s17, 0x1c000
	v_lshl_add_u64 v[2:3], s[0:1], 0, v[0:1]
	global_load_lds_dwordx4 v[2:3], off
	v_lshl_add_u64 v[2:3], s[0:1], 0, v[134:135]
	s_add_i32 m0, s17, 0x1e000
	v_lshlrev_b32_e32 v19, 3, v18
	global_load_lds_dwordx4 v[2:3], off
	s_cmp_lg_u32 s38, 1
	s_cbranch_scc1 .LBB0_660
	s_barrier
.LBB0_660:
	s_waitcnt vmcnt(8)
	s_barrier
	v_lshlrev_b32_e32 v2, 15, v10
	v_and_b32_e32 v2, 0xffff0000, v2
	v_lshl_add_u32 v2, v11, 12, v2
	v_and_b32_e32 v3, 1, v10
	v_lshl_or_b32 v2, v3, 6, v2
	v_lshl_add_u32 v136, v12, 1, v2
	v_lshlrev_b32_e32 v2, 15, v13
	v_and_b32_e32 v2, 0xffff0000, v2
	s_waitcnt vmcnt(6)
	v_lshl_add_u32 v2, v14, 12, v2
	v_and_b32_e32 v3, 1, v13
	s_cmpk_lt_u32 s20, 0x100
	v_lshl_or_b32 v2, v3, 6, v2
	s_cselect_b64 s[48:49], -1, 0
	v_lshl_or_b32 v148, s82, 6, v19
	s_mov_b32 s85, 0
	v_cmp_eq_u32_e64 s[38:39], 0, v18
	v_mov_b32_e32 v137, v1
	v_lshl_add_u32 v138, v15, 1, v2
	v_mov_b32_e32 v139, v1
	v_add_u32_e32 v149, 0, v20
	s_barrier
	s_branch .LBB0_663

; #define PG8_STAGE(bufoff, gbase, voff) do { _Pragma("unroll") for (int _i = 0; _i < 2; ++_i) \
;         __builtin_amdgcn_global_load_lds((const __attribute__((address_space(1))) unsigned*)((const char*)(gbase) + (voff)[_i]), (LAS unsigned*)(lds + (bufoff) + ldsw + _i * 8192), 16, 0, 0); } while (0)
; #define PG8_WAIT_V(n) asm volatile("s_waitcnt vmcnt(" #n ")" ::: "memory")
; #define PG8_BAR __builtin_amdgcn_s_barrier()
; template <class Epi, class SchedT, bool ALIGN_EPI, bool SP2>
; __device__ __forceinline__ void gemm_phase(LAS unsigned char* lds, const int ldk, const int nt, const SchedT& S, const Epi& E) {
;     ...
;     for (int i = 0; i < 2; ++i) { int R, C; stage_rc(tid * 16 + i * 8192, R, C); const int Rb = 2 * (R & ~31) + perm32(R & 31);
;         voffA[i] = (unsigned)(R * K + C) * 2u; voffB[i] = (unsigned)(Rb * K + C) * 2u; }
;     const size_t kstep = (size_t)(BK * 2);
;     const size_t hstep = (size_t)HALF * K * 2;
;     const size_t hstepB = (size_t)32 * K * 2;
;     const unsigned ldsw = (unsigned)wid * 1024u;
;     const int aoff = lds_byte(wr * 64 + fr, fq * 8), boff = lds_byte(wc * 32 + fr, fq * 8);
;     ...
;     if constexpr (SP2) {
;         PG8_STAGE(PG8_SB(0, 0), cB, voffB); PG8_STAGE(PG8_SB(0, 1), cB + hstepB, voffB); PG8_STAGE(PG8_SA(0, 0), cA, voffA); PG8_STAGE(PG8_SA(0, 1), cA + hstep, voffA);
;         if (wr == 1) PG8_BAR;
;         PG8_WAIT_V(2); PG8_BAR;
;         PG8_STAGE(PG8_SB(1, 0), cB + kstep, voffB); PG8_STAGE(PG8_SA(1, 0), cA + kstep, voffA); PG8_STAGE(PG8_SB(1, 1), cB + hstepB + kstep, voffB);
;         PG8_WAIT_V(6); PG8_BAR;
.LBB0_741:
	v_readlane_b32 s18, v163, 39
	v_readlane_b32 s44, v254, 1
	s_mul_i32 s13, s18, 0x20400
	v_readlane_b32 s52, v254, 9
	v_readlane_b32 s19, v163, 40
	s_mov_b32 s20, s18
	v_readlane_b32 s53, v254, 10
	s_add_u32 s18, s52, s13
	v_readlane_b32 s54, v254, 11
	s_addc_u32 s19, s53, 0
	s_mul_i32 s13, s20, 0xac00
	v_readlane_b32 s55, v254, 12
	s_add_u32 s20, s54, s13
	s_addc_u32 s21, s55, 0
	s_and_b64 vcc, exec, s[0:1]
	v_readlane_b32 s45, v254, 2
	v_readlane_b32 s46, v254, 3
	v_readlane_b32 s47, v254, 4
	v_readlane_b32 s48, v254, 5
	v_readlane_b32 s49, v254, 6
	v_readlane_b32 s50, v254, 7
	v_readlane_b32 s51, v254, 8
	v_readlane_b32 s56, v254, 13
	v_readlane_b32 s57, v254, 14
	v_readlane_b32 s58, v254, 15
	v_readlane_b32 s59, v254, 16
	s_cbranch_vccnz .LBB0_791
	v_ashrrev_i32_e32 v0, 31, v16
	v_lshrrev_b32_e32 v0, 26, v0
	v_add_u32_e32 v0, v16, v0
	v_ashrrev_i32_e32 v10, 6, v0
	v_bfe_i32 v0, v16, 27, 1
	v_lshlrev_b32_e32 v2, 4, v16
	v_lshrrev_b32_e32 v0, 22, v0
	v_add_u32_e32 v0, v2, v0
	v_and_b32_e32 v0, 0xfffffc00, v0
	v_sub_u32_e32 v0, v2, v0
	v_lshrrev_b32_e32 v3, 4, v0
	v_bitop3_b32 v0, v3, v0, 32 bitop3:0x6c
	v_ashrrev_i32_e32 v4, 31, v0
	v_lshrrev_b32_e32 v4, 26, v4
	v_add_u32_e32 v4, v0, v4
	v_lshlrev_b32_e32 v3, 3, v10
	v_ashrrev_i32_e32 v11, 6, v4
	v_and_b32_e32 v4, 0xc0, v4
	v_and_b32_e32 v3, -16, v3
	v_sub_u32_e32 v0, v0, v4
	v_add_u32_e32 v3, v11, v3
	v_ashrrev_i16_sdwa v0, v244, sext(v0) dst_sel:DWORD dst_unused:UNUSED_PAD src0_sel:DWORD src1_sel:BYTE_0
	v_lshlrev_b32_e32 v5, 5, v10
	v_bfe_i32 v12, v0, 0, 16
	v_lshlrev_b32_e32 v0, 1, v3
	v_lshrrev_b32_e32 v4, 2, v3
	v_and_b32_e32 v5, 32, v5
	v_and_b32_e32 v4, 4, v4
	v_and_b32_e32 v6, 3, v11
	v_and_b32_e32 v0, 0xfffd8, v0
	v_or3_b32 v0, v6, v4, v0
	v_add_lshl_u32 v4, v5, v12, 1
	v_add_u32_e32 v2, 0x2000, v2
	v_lshl_add_u32 v146, v3, 12, v4
	v_ashrrev_i32_e32 v3, 31, v2
	v_lshrrev_b32_e32 v3, 22, v3
	v_add_u32_e32 v3, v2, v3
	v_ashrrev_i32_e32 v13, 10, v3
	v_mul_i32_i24_e32 v3, 0x400, v13
	v_readlane_b32 s0, v163, 36
	v_sub_u32_e32 v2, v2, v3
	s_add_u32 s0, s38, s0
	v_lshrrev_b32_e32 v3, 4, v2
	s_addc_u32 s1, s39, 0
	v_bitop3_b32 v2, v3, v2, 32 bitop3:0x6c
	s_add_u32 s22, s38, 0x10c00000
	v_lshl_add_u32 v0, v0, 12, v4
	v_ashrrev_i32_e32 v4, 31, v2
	s_addc_u32 s81, s39, 0
	v_lshrrev_b32_e32 v4, 26, v4
	s_add_u32 s82, s0, 0x3600000
	v_add_u32_e32 v4, v2, v4
	s_addc_u32 s83, s1, 0
	v_lshlrev_b32_e32 v3, 3, v13
	v_ashrrev_i32_e32 v14, 6, v4
	v_and_b32_e32 v4, 0xc0, v4
	s_ashr_i32 s41, s40, 6
	s_ashr_i32 s13, s12, 31
	s_ashr_i32 s17, s16, 31
	s_ashr_i32 s50, s40, 8
	v_and_b32_e32 v3, -16, v3
	v_sub_u32_e32 v2, v2, v4
	s_lshl_b32 s84, s41, 10
	s_lshl_b64 s[0:1], s[12:13], 20
	s_lshl_b64 s[34:35], s[16:17], 20
	v_add_u32_e32 v3, v14, v3
	v_ashrrev_i16_sdwa v2, v244, sext(v2) dst_sel:DWORD dst_unused:UNUSED_PAD src0_sel:DWORD src1_sel:BYTE_0
	s_add_u32 s36, s82, s34
	v_lshlrev_b32_e32 v5, 5, v13
	v_bfe_i32 v15, v2, 0, 16
	v_lshlrev_b32_e32 v2, 1, v3
	v_lshrrev_b32_e32 v4, 2, v3
	s_addc_u32 s37, s83, s35
	s_add_i32 s85, s84, 0
	v_and_b32_e32 v5, 32, v5
	v_and_b32_e32 v4, 4, v4
	v_and_b32_e32 v6, 3, v14
	v_and_b32_e32 v2, 0xfffd8, v2
	s_add_i32 m0, s85, 0x10000
	v_or3_b32 v2, v6, v4, v2
	v_add_lshl_u32 v4, v5, v15, 1
	global_load_lds_dwordx4 v0, s[36:37]
	s_add_i32 m0, s85, 0x12000
	v_lshl_add_u32 v150, v2, 12, v4
	s_add_u32 s34, s36, 0x20000
	global_load_lds_dwordx4 v150, s[36:37]
	s_addc_u32 s35, s37, 0
	s_add_i32 m0, s85, 0x14000
	v_lshl_add_u32 v148, v3, 12, v4
	global_load_lds_dwordx4 v0, s[34:35]
	s_add_i32 m0, s85, 0x16000
	v_mov_b32_e32 v151, v1
	global_load_lds_dwordx4 v150, s[34:35]
	s_add_u32 s34, s22, s0
	s_addc_u32 s35, s81, s1
	s_add_i32 s86, s85, 0x2000
	s_mov_b32 m0, s85
	s_add_u32 s0, s34, 0x80000
	global_load_lds_dwordx4 v146, s[34:35]
	s_mov_b32 m0, s86
	s_addc_u32 s1, s35, 0
	s_add_i32 s87, s85, 0x4000
	global_load_lds_dwordx4 v148, s[34:35]
	s_mov_b32 m0, s87
	s_add_i32 s88, s85, 0x6000
	global_load_lds_dwordx4 v146, s[0:1]
	s_mov_b32 m0, s88
	v_mov_b32_e32 v147, v1
	global_load_lds_dwordx4 v148, s[0:1]
	v_mov_b32_e32 v149, v1
	s_cmp_eq_u32 s50, 1
	v_mov_b32_e32 v162, v242
	v_lshl_add_u64 v[8:9], s[36:37], 0, v[0:1]
	v_lshl_add_u64 v[6:7], s[36:37], 0, v[150:151]
	v_lshl_add_u64 v[2:3], s[34:35], 0, v[146:147]
	s_cselect_b64 s[52:53], -1, 0
	v_lshl_add_u64 v[4:5], s[34:35], 0, v[148:149]
	s_lshl_b64 s[0:1], s[30:31], 2
	s_add_u32 s0, s38, s0
	s_addc_u32 s1, s39, s1
	s_add_u32 s30, s38, 0x21800000
	v_lshrrev_b32_e32 v17, 1, v16
	s_addc_u32 s31, s39, 0
	v_and_b32_e32 v17, 24, v17
	s_add_u32 s54, s38, 0x28200000
	v_and_b32_e32 v246, 15, v16
	v_lshlrev_b32_e32 v18, 1, v17
	v_lshlrev_b32_e32 v16, 2, v16
	s_addc_u32 s55, s39, 0
	v_lshl_or_b32 v18, v246, 6, v18
	s_lshl_b32 s13, s50, 13
	v_and_b32_e32 v16, 32, v16
	v_bitop3_b32 v19, v18, s13, v16 bitop3:0xde
	s_lshl_b32 s13, s41, 5
	s_and_b32 s13, s13, 0x60
	s_add_i32 m0, s85, 0x18000
	v_lshl_add_u64 v[8:9], v[8:9], 0, s[24:25]
	s_lshl_b32 s17, s13, 7
	global_load_lds_dwordx4 v[8:9], off
	v_lshl_add_u64 v[6:7], v[6:7], 0, s[24:25]
	s_add_i32 m0, s85, 0x1a000
	s_add_i32 s89, s85, 0x8000
	s_add_i32 s90, s85, 0xa000
	global_load_lds_dwordx4 v[6:7], off
	v_lshl_add_u64 v[2:3], v[2:3], 0, s[24:25]
	s_mov_b32 m0, s89
	s_add_u32 s38, s36, 0x20080
	global_load_lds_dwordx4 v[2:3], off
	v_lshl_add_u64 v[2:3], v[4:5], 0, s[24:25]
	s_mov_b32 m0, s90
	s_addc_u32 s39, s37, 0
	global_load_lds_dwordx4 v[2:3], off
	s_add_i32 m0, s85, 0x1c000
	v_lshl_add_u64 v[2:3], s[38:39], 0, v[0:1]
	global_load_lds_dwordx4 v[2:3], off
	v_lshl_add_u64 v[2:3], s[38:39], 0, v[150:151]
	s_add_i32 m0, s85, 0x1e000
	s_cmpk_lt_u32 s40, 0x100
	global_load_lds_dwordx4 v[2:3], off
	s_cmp_lg_u32 s50, 1
	s_cbranch_scc1 .LBB0_744
	s_barrier
.LBB0_744:
	s_waitcnt vmcnt(8)
	s_barrier
	v_lshlrev_b32_e32 v2, 2, v17
	v_mov_b32_e32 v3, v1
	v_lshl_add_u64 v[2:3], s[0:1], 0, v[2:3]
	s_mov_b64 s[0:1], 0x27c00000
	v_lshl_add_u64 v[152:153], v[2:3], 0, s[0:1]
	v_lshlrev_b32_e32 v2, 15, v10
	v_and_b32_e32 v2, 0xffff0000, v2
	v_lshl_add_u32 v2, v11, 12, v2
	v_and_b32_e32 v3, 1, v10
	v_lshl_or_b32 v2, v3, 6, v2
	v_lshl_add_u32 v154, v12, 1, v2
	v_lshlrev_b32_e32 v2, 15, v13
	v_and_b32_e32 v2, 0xffff0000, v2
	s_waitcnt vmcnt(6)
	v_lshl_add_u32 v2, v14, 12, v2
	v_and_b32_e32 v3, 1, v13
	v_lshl_or_b32 v2, v3, 6, v2
	v_lshl_or_b32 v247, s50, 6, v246
	v_bitop3_b32 v248, v18, s17, v16 bitop3:0xde
	s_cselect_b64 s[56:57], -1, 0
	v_cmp_eq_u32_e64 s[38:39], 15, v246
	v_cmp_ne_u32_e64 s[40:41], 15, v246
	s_mov_b32 s91, 0
	v_cmp_eq_u32_e64 s[42:43], 0, v246
	v_cmp_ne_u32_e64 s[44:45], 0, v246
	v_cmp_gt_u32_e64 s[46:47], 2, v246
	v_cmp_lt_u32_e64 s[48:49], 13, v246
	v_add_u32_e32 v249, -12, v246
	s_lshl_b32 s92, s50, 2
	v_or_b32_e32 v250, s13, v17
	v_mov_b32_e32 v155, v1
	v_lshl_add_u32 v156, v15, 1, v2
	v_mov_b32_e32 v157, v1
	v_add_u32_e32 v251, 0, v19
	s_movk_i32 s80, 0x5600
	s_barrier
	s_branch .LBB0_747
